# v16 + barrier census: 16 counter loads issued together (were 16 serialized round trips) + MINI loop software-pipelined (next trip's row loads issued before this trip's compute, counted vmcnt(8))
# speedup vs baseline: 1.0134x; 1.0034x over previous
; __device__ __forceinline__ unsigned xb_ld(unsigned* p)              { return __hip_atomic_load(p, __ATOMIC_RELAXED, __HIP_MEMORY_SCOPE_AGENT); }
; __device__ __forceinline__ void xcd_barrier_complete(unsigned* bar, unsigned x, unsigned& nloc, unsigned& nx) {
;     const unsigned G = gridDim.x * gridDim.y * gridDim.z;
;     unsigned sum, cnt, mine, sp = 0u;
;     for (;;) {
;         sum = 0u; cnt = 0u; mine = 0u;
; #pragma unroll
;         for (unsigned j = 0; j < 16; ++j) { const unsigned c = xb_ld(&bar[XB_XCNT(j)]); sum += c; cnt += (c > 0u) ? 1u : 0u; mine = (j == x) ? c : mine; }
;         if (sum == G) break;
;         __builtin_amdgcn_s_sleep(1);
;         if ((++sp & 255u) == 0u) { if (xb_ld(&bar[XB_TMO])) break; if (sp > XB_SPIN_CAP) { atomicAdd(&bar[XB_TMO], 1u); break; } }
;     }
;     nloc = mine > 0u ? mine : 1u; nx = cnt > 0u ? cnt : 1u;
.LBB0_128:
	v_readlane_b32 s6, v252, 4
	v_readlane_b32 s7, v252, 5
	s_mov_b64 s[8:9], -1
	s_waitcnt lgkmcnt(0)
	s_nop 4
	global_load_dword v0, v5, s[6:7] sc1
	global_load_dword v1, v5, s[6:7] offset:256 sc1
	global_load_dword v2, v5, s[6:7] offset:512 sc1
	global_load_dword v3, v5, s[6:7] offset:768 sc1
	global_load_dword v4, v5, s[6:7] offset:1024 sc1
	global_load_dword v6, v5, s[6:7] offset:1280 sc1
	global_load_dword v7, v5, s[6:7] offset:1536 sc1
	global_load_dword v8, v5, s[6:7] offset:1792 sc1
	global_load_dword v9, v5, s[6:7] offset:2048 sc1
	global_load_dword v10, v5, s[6:7] offset:2304 sc1
	global_load_dword v11, v5, s[6:7] offset:2560 sc1
	global_load_dword v12, v5, s[6:7] offset:2816 sc1
	global_load_dword v13, v5, s[6:7] offset:3072 sc1
	global_load_dword v14, v5, s[6:7] offset:3328 sc1
	global_load_dword v15, v5, s[6:7] offset:3584 sc1
	global_load_dword v16, v5, s[6:7] offset:3840 sc1
	s_nop 0
	s_mov_b64 s[6:7], -1
	s_waitcnt vmcnt(0)
	v_add_u32_e32 v17, v1, v0
	v_add_u32_e32 v17, v17, v2
	v_add_u32_e32 v17, v17, v3
	v_add_u32_e32 v17, v17, v4
	v_add_u32_e32 v17, v17, v6
	v_add_u32_e32 v17, v17, v7
	v_add_u32_e32 v17, v17, v8
	v_add_u32_e32 v17, v17, v9
	v_add_u32_e32 v17, v17, v10
	v_add_u32_e32 v17, v17, v11
	v_add_u32_e32 v17, v17, v12
	v_add_u32_e32 v17, v17, v13
	v_add_u32_e32 v17, v17, v14
	v_add_u32_e32 v17, v17, v15
	v_add_u32_e32 v17, v17, v16
	v_cmp_eq_u32_e32 vcc, s85, v17
	s_cbranch_vccnz .LBB0_127
	s_and_b32 s6, s12, 0xff
	s_cmp_eq_u32 s6, 0
	s_mov_b64 s[6:7], -1
	s_mov_b64 s[10:11], -1
	s_sleep 1
	s_cbranch_scc1 .LBB0_132
	s_and_b64 vcc, exec, s[10:11]
	s_cbranch_vccz .LBB0_127

; __device__ __forceinline__ float bf1(bf16_t h) { return __uint_as_float(((unsigned)h) << 16); }
; #define INPTR(k) ({ int _i = (k); asm volatile("" : "+s"(_i)); (const float*)(GAS const float*)a.in[_i]; })
; __global__ void __launch_bounds__(512, 2) mega(Args a) {
;     ...
;                 const float* gq = INPTR(5) + (size_t)l * 384; const float* gkv = INPTR(7) + (size_t)l * 256;
;                 for (int m0 = gw * 2; m0 < Tc; m0 += NGW * 2) {
;                     u32x4 wq[2], wk[2]; float x1[2], x2[2]; f32x2 cs[2];
; #pragma unroll
;                     for (int rr = 0; rr < 2; ++rr) { const int m = m0 + rr; bf16_t* P = PROJ + (size_t)m * INP;
;                         wq[rr] = (u32x4){0u, 0u, 0u, 0u}; wk[rr] = (u32x4){0u, 0u, 0u, 0u}; x1[rr] = 0.f; x2[rr] = 0.f; cs[rr] = (f32x2){0.f, 0.f};
;                         if (lane < 48) wq[rr] = *(const u32x4*)(P + C_CQ + lane * 8);
;                         if (lane < 32) wk[rr] = *(const u32x4*)(P + C_CKV + lane * 8);
;                         if (lane < 16) { x1[rr] = bf1(P[C_KPE + lane]); x2[rr] = bf1(P[C_KPE + 16 + lane]); cs[rr] = rope[(m & (SEQ - 1)) * 16 + lane]; } }
.LBB0_1523:
	s_and_b64 vcc, exec, s[4:5]
	s_cbranch_vccz .LBB0_1551
	s_lshl_b32 s4, s83, 1
	s_mov_b32 s10, 5
	s_mov_b32 s8, 7
	s_cmp_ge_i32 s4, s16
	s_cbranch_scc1 .LBB0_1551
	s_ashr_i32 s11, s10, 31
	s_lshl_b64 s[6:7], s[10:11], 3
	s_add_u32 s6, s0, s6
	s_addc_u32 s7, s1, s7
	s_ashr_i32 s9, s8, 31
	s_lshl_b64 s[8:9], s[8:9], 3
	s_add_u32 s8, s0, s8
	s_addc_u32 s9, s1, s9
	s_load_dwordx2 s[8:9], s[8:9], 0x0
	v_readlane_b32 s12, v253, 50
	s_load_dwordx2 s[6:7], s[6:7], 0x0
	v_readlane_b32 s13, v253, 51
	s_lshl_b64 s[10:11], s[12:13], 10
	s_waitcnt lgkmcnt(0)
	s_add_u32 s8, s8, s10
	s_addc_u32 s9, s9, s11
	s_mul_i32 s10, s12, 0x600
	s_mul_hi_i32 s5, s12, 0x600
	s_add_u32 s6, s6, s10
	v_cmp_lt_i32_e32 vcc, v185, v184
	s_addc_u32 s7, s7, s5
	v_lshlrev_b32_e32 v4, 5, v203
	v_cndmask_b32_e32 v0, v183, v185, vcc
	v_cmp_lt_i32_e32 vcc, v186, v184
	v_lshlrev_b32_e32 v39, 2, v0
	v_lshl_add_u64 v[20:21], s[6:7], 0, v[4:5]
	v_cndmask_b32_e32 v0, v183, v186, vcc
	v_cmp_lt_i32_e32 vcc, v187, v184
	v_lshl_add_u64 v[22:23], s[8:9], 0, v[4:5]
	s_mul_i32 s6, s4, 0x3600
	v_readlane_b32 s8, v253, 60
	v_lshlrev_b32_e32 v40, 2, v0
	v_cndmask_b32_e32 v0, v183, v187, vcc
	v_cmp_lt_i32_e32 vcc, v188, v184
	s_mul_hi_i32 s5, s4, 0x3600
	v_readlane_b32 s9, v253, 61
	s_add_u32 s6, s6, s8
	v_lshlrev_b32_e32 v41, 2, v0
	v_cndmask_b32_e32 v0, v183, v188, vcc
	v_cmp_lt_i32_e32 vcc, v189, v184
	s_addc_u32 s5, s5, s9
	v_lshlrev_b32_e32 v42, 2, v0
	v_cndmask_b32_e32 v0, v183, v189, vcc
	v_cmp_lt_i32_e32 vcc, v190, v184
	s_add_u32 s8, s74, s6
	v_lshlrev_b32_e32 v43, 2, v0
	v_cndmask_b32_e32 v0, v183, v190, vcc
	s_addc_u32 s9, s75, s5
	s_lshl_b32 s5, s92, 5
	v_readlane_b32 s6, v253, 16
	v_cmp_gt_u32_e64 s[40:41], 48, v203
	v_cmp_gt_u32_e64 s[42:43], 32, v203
	v_cmp_gt_u32_e64 s[44:45], 16, v203
	v_lshlrev_b32_e32 v44, 2, v0
	v_lshlrev_b32_e32 v24, 4, v203
	v_mov_b32_e32 v25, v5
	v_lshlrev_b32_e32 v26, 1, v203
	v_mov_b32_e32 v27, v5
	s_add_i32 s5, s6, s5
	v_mov_b32_e32 v64, 0
	v_mov_b32_e32 v65, 0
	v_mov_b32_e32 v66, 0
	v_mov_b32_e32 v67, 0
	v_mov_b32_e32 v68, 0
	v_mov_b32_e32 v69, 0
	v_mov_b32_e32 v70, 0
	v_mov_b32_e32 v71, 0
	v_mov_b32_e32 v72, 0
	v_mov_b32_e32 v73, 0
	v_mov_b32_e32 v74, 0
	v_mov_b32_e32 v75, 0
	v_mov_b32_e32 v76, 0
	v_mov_b32_e32 v77, 0
	v_mov_b32_e32 v78, 0
	v_mov_b32_e32 v79, 0
	s_and_saveexec_b64 s[10:11], s[40:41]
	global_load_dwordx4 v[64:67], v[20:21], off
	global_load_dwordx4 v[68:71], v[20:21], off offset:16
	s_mov_b64 exec, s[10:11]
	s_and_saveexec_b64 s[10:11], s[42:43]
	global_load_dwordx4 v[72:75], v[22:23], off
	global_load_dwordx4 v[76:79], v[22:23], off offset:16
	s_mov_b64 exec, s[10:11]
	v_mov_b32_e32 v80, 0
	v_mov_b32_e32 v81, 0
	v_mov_b32_e32 v82, 0
	v_mov_b32_e32 v83, 0
	v_mov_b32_e32 v84, 0
	v_mov_b32_e32 v85, 0
	v_mov_b32_e32 v86, 0
	v_mov_b32_e32 v87, 0
	v_mov_b32_e32 v88, 0
	v_mov_b32_e32 v89, 0
	v_mov_b32_e32 v90, 0
	v_mov_b32_e32 v91, 0
	v_mov_b32_e32 v92, 0
	v_mov_b32_e32 v93, 0
	v_mov_b32_e32 v94, 0
	v_mov_b32_e32 v95, 0
	v_mov_b32_e32 v96, 0
	v_mov_b32_e32 v97, 0
	v_mov_b32_e32 v98, 0
	v_mov_b32_e32 v99, 0
	v_mov_b32_e32 v100, 0
	v_mov_b32_e32 v101, 0
	v_mov_b32_e32 v102, 0
	v_mov_b32_e32 v103, 0
	v_lshl_add_u64 v[28:29], s[8:9], 0, v[24:25]
	v_lshl_add_u64 v[30:31], s[8:9], 0, v[26:27]
	v_mov_b32_e32 v8, 0
	v_mov_b32_e32 v9, 0
	v_mov_b32_e32 v10, 0
	v_mov_b32_e32 v11, 0
	v_mov_b32_e32 v12, 0
	v_mov_b32_e32 v13, 0
	v_mov_b32_e32 v14, 0
	v_mov_b32_e32 v15, 0
	v_mov_b32_e32 v16, 0
	v_mov_b32_e32 v17, 0
	v_mov_b32_e32 v18, 0
	v_mov_b32_e32 v19, 0
	v_mov_b32_e32 v0, 0
	v_mov_b32_e32 v1, 0
	v_mov_b32_e32 v2, 0
	v_mov_b32_e32 v3, 0
	v_mov_b32_e32 v36, 0
	v_mov_b32_e32 v37, 0
	v_mov_b32_e32 v34, 0
	v_mov_b32_e32 v35, 0
	v_mov_b32_e32 v58, 0
	v_mov_b32_e32 v59, 0
	v_mov_b32_e32 v60, 0
	v_mov_b32_e32 v61, 0
	v_add_co_u32_e32 v50, vcc, 0x5003000, v28
	s_nop 1
	v_addc_co_u32_e32 v51, vcc, 0, v29, vcc
	v_add_co_u32_e32 v52, vcc, 0x5006000, v28
	s_nop 1
	v_addc_co_u32_e32 v53, vcc, 0, v29, vcc
	v_add_co_u32_e32 v54, vcc, 0x5003000, v30
	s_nop 1
	v_addc_co_u32_e32 v55, vcc, 0, v31, vcc
	v_add_co_u32_e32 v56, vcc, 0x5006000, v30
	s_nop 1
	v_addc_co_u32_e32 v57, vcc, 0, v31, vcc
	s_and_b32 s6, s5, 0x7fe0
	v_or_b32_e32 v4, s6, v203
	v_lshlrev_b32_e32 v4, 3, v4
	s_add_i32 s6, s5, 16
	s_and_b32 s6, s6, 0x7ff0
	v_or_b32_e32 v6, s6, v203
	v_lshlrev_b32_e32 v6, 3, v6
	v_mov_b32_e32 v7, 0
	v_readlane_b32 s6, v253, 42
	v_readlane_b32 s7, v253, 43
	s_nop 1
	v_lshl_add_u64 v[62:63], s[6:7], 0, v[4:5]
	v_lshl_add_u64 v[46:47], s[6:7], 0, v[6:7]
	s_and_saveexec_b64 s[10:11], s[40:41]
	global_load_dwordx4 v[8:11], v[50:51], off
	global_load_dwordx4 v[12:15], v[52:53], off offset:1536
	s_mov_b64 exec, s[10:11]
	s_and_saveexec_b64 s[10:11], s[42:43]
	global_load_dwordx4 v[16:19], v[50:51], off offset:768
	global_load_dwordx4 v[0:3], v[52:53], off offset:2304
	s_mov_b64 exec, s[10:11]
	s_and_saveexec_b64 s[10:11], s[44:45]
	global_load_ushort v58, v[54:55], off offset:1280
	global_load_ushort v59, v[54:55], off offset:1312
	global_load_ushort v60, v[56:57], off offset:2816
	global_load_ushort v61, v[56:57], off offset:2848
	global_load_dwordx2 v[36:37], v[62:63], off
	global_load_dwordx2 v[34:35], v[46:47], off
	s_mov_b64 exec, s[10:11]
	s_waitcnt vmcnt(0)
	v_lshlrev_b32_e32 v38, 16, v58
	v_lshlrev_b32_e32 v32, 16, v59
	v_lshlrev_b32_e32 v7, 16, v60
	v_lshlrev_b32_e32 v33, 16, v61
	s_branch .LBB0_1527
; __device__ __forceinline__ float bf1(bf16_t h) { return __uint_as_float(((unsigned)h) << 16); }
; __global__ void __launch_bounds__(512, 2) mega(Args a) {
;     ...
;                 for (int m0 = gw * 2; m0 < Tc; m0 += NGW * 2) {
;                     u32x4 wq[2], wk[2]; float x1[2], x2[2]; f32x2 cs[2];
; #pragma unroll
;                     for (int rr = 0; rr < 2; ++rr) { const int m = m0 + rr; bf16_t* P = PROJ + (size_t)m * INP;
;                         wq[rr] = (u32x4){0u, 0u, 0u, 0u}; wk[rr] = (u32x4){0u, 0u, 0u, 0u}; x1[rr] = 0.f; x2[rr] = 0.f; cs[rr] = (f32x2){0.f, 0.f};
;                         if (lane < 48) wq[rr] = *(const u32x4*)(P + C_CQ + lane * 8);
;                         if (lane < 32) wk[rr] = *(const u32x4*)(P + C_CKV + lane * 8);
;                         if (lane < 16) { x1[rr] = bf1(P[C_KPE + lane]); x2[rr] = bf1(P[C_KPE + 16 + lane]); cs[rr] = rope[(m & (SEQ - 1)) * 16 + lane]; } }
.LBB0_1526:
	s_or_b64 exec, exec, s[10:11]
	s_add_i32 s4, s4, s94
	s_mul_i32 s6, s76, 0x36000
	s_add_u32 s8, s8, s6
	s_mul_hi_i32 s6, s94, 0x3600
	s_addc_u32 s9, s9, s6
	v_readlane_b32 s6, v253, 17
	s_add_i32 s5, s5, s6
	s_cmp_ge_i32 s4, s16
	s_cbranch_scc1 .LBB0_1551
	s_waitcnt vmcnt(8)
	v_mov_b32_e32 v8, v80
	v_mov_b32_e32 v9, v81
	v_mov_b32_e32 v10, v82
	v_mov_b32_e32 v11, v83
	v_mov_b32_e32 v12, v84
	v_mov_b32_e32 v13, v85
	v_mov_b32_e32 v14, v86
	v_mov_b32_e32 v15, v87
	v_mov_b32_e32 v16, v88
	v_mov_b32_e32 v17, v89
	v_mov_b32_e32 v18, v90
	v_mov_b32_e32 v19, v91
	v_mov_b32_e32 v0, v92
	v_mov_b32_e32 v1, v93
	v_mov_b32_e32 v2, v94
	v_mov_b32_e32 v3, v95
	v_mov_b32_e32 v36, v100
	v_mov_b32_e32 v37, v101
	v_mov_b32_e32 v34, v102
	v_mov_b32_e32 v35, v103
	v_lshlrev_b32_e32 v38, 16, v96
	v_lshlrev_b32_e32 v32, 16, v97
	v_lshlrev_b32_e32 v7, 16, v98
	v_lshlrev_b32_e32 v33, 16, v99
.LBB0_1527:
	v_lshl_add_u64 v[28:29], s[8:9], 0, v[24:25]
	v_lshl_add_u64 v[30:31], s[8:9], 0, v[26:27]
	s_add_i32 s7, s4, s94
	s_cmp_lt_i32 s7, s16
	s_cbranch_scc0 .Lmy_mini_nopf
	s_mul_i32 s6, s76, 0x36000
	s_mul_hi_i32 s7, s94, 0x3600
	v_lshl_add_u64 v[104:105], v[28:29], 0, s[6:7]
	v_lshl_add_u64 v[106:107], v[30:31], 0, s[6:7]
	v_add_co_u32_e32 v108, vcc, 0x5003000, v104
	s_nop 1
	v_addc_co_u32_e32 v109, vcc, 0, v105, vcc
	v_add_co_u32_e32 v110, vcc, 0x5006000, v104
	s_nop 1
	v_addc_co_u32_e32 v111, vcc, 0, v105, vcc
	v_add_co_u32_e32 v112, vcc, 0x5003000, v106
	s_nop 1
	v_addc_co_u32_e32 v113, vcc, 0, v107, vcc
	v_add_co_u32_e32 v114, vcc, 0x5006000, v106
	s_nop 1
	v_addc_co_u32_e32 v115, vcc, 0, v107, vcc
	v_readlane_b32 s6, v253, 17
	s_nop 0
	s_add_i32 s6, s5, s6
	s_and_b32 s7, s6, 0x7fe0
	v_or_b32_e32 v120, s7, v203
	v_lshlrev_b32_e32 v120, 3, v120
	s_add_i32 s7, s6, 16
	s_and_b32 s7, s7, 0x7ff0
	v_or_b32_e32 v122, s7, v203
	v_lshlrev_b32_e32 v122, 3, v122
	v_mov_b32_e32 v121, 0
	v_mov_b32_e32 v123, 0
	v_readlane_b32 s6, v253, 42
	v_readlane_b32 s7, v253, 43
	s_nop 1
	v_lshl_add_u64 v[116:117], s[6:7], 0, v[120:121]
	v_lshl_add_u64 v[118:119], s[6:7], 0, v[122:123]
	s_and_saveexec_b64 s[10:11], s[40:41]
	global_load_dwordx4 v[80:83], v[108:109], off
	global_load_dwordx4 v[84:87], v[110:111], off offset:1536
	s_mov_b64 exec, s[10:11]
	s_and_saveexec_b64 s[10:11], s[42:43]
	global_load_dwordx4 v[88:91], v[108:109], off offset:768
	global_load_dwordx4 v[92:95], v[110:111], off offset:2304
	s_mov_b64 exec, s[10:11]
	s_and_saveexec_b64 s[10:11], s[44:45]
	global_load_ushort v96, v[112:113], off offset:1280
	global_load_ushort v97, v[112:113], off offset:1312
	global_load_ushort v98, v[114:115], off offset:2816
	global_load_ushort v99, v[114:115], off offset:2848
	global_load_dwordx2 v[100:101], v[116:117], off
	global_load_dwordx2 v[102:103], v[118:119], off
	s_mov_b64 exec, s[10:11]
.Lmy_mini_nopf:
	s_mov_b64 s[10:11], exec
